# first K-iteration peeled with C=0 first-touch MFMAs (no accumulator zeroing) in FFN-up and w_in GEMMs; plus hand-written epilogue fast paths, LRU prefetch, sc1 stores
# speedup vs baseline: 1.0373x; 1.0103x over previous
; #define PG8_STAGE(bufoff, gbase, voff) do { _Pragma("unroll") for (int _i = 0; _i < 2; ++_i) \
;         __builtin_amdgcn_global_load_lds((const unsigned*)((const char*)(gbase) + (voff)[_i]), (PG8_LAS unsigned*)(lds + (bufoff) + ldsw + _i * 8192), 16, 0, 0); } while (0)
; #define PG8_LDA(dst, b, h) do { _Pragma("unroll") for (int m = 0; m < 4; ++m) _Pragma("unroll") for (int k = 0; k < 2; ++k) dst[m][k] = *(const PG8_LAS bf16x8*)(lds + PG8_SA(b, h) + aoff + m * 2048 + k * 1024); } while (0)
; #define PG8_LDB(dst, b, h) do { _Pragma("unroll") for (int n = 0; n < 2; ++n) _Pragma("unroll") for (int k = 0; k < 2; ++k) dst[n][k] = *(const PG8_LAS bf16x8*)(lds + PG8_SB(b, h) + boff + n * 2048 + k * 1024); } while (0)
; #define PG8_MMA(ai, bj, At, Bt) do { __builtin_amdgcn_s_setprio(1); _Pragma("unroll") for (int m = 0; m < 4; ++m) _Pragma("unroll") for (int n = 0; n < 2; ++n) _Pragma("unroll") for (int k = 0; k < 2; ++k) \
;         acc[ai][bj][m][n] = __builtin_amdgcn_mfma_f32_16x16x32_bf16(Bt[n][k], At[m][k], acc[ai][bj][m][n], 0, 0, 0); __builtin_amdgcn_s_setprio(0); } while (0)
; #define PG8_WAIT_V(n) asm volatile("s_waitcnt vmcnt(" #n ")" ::: "memory")
; template <class Epi, class Sched, bool ALIGN_EPI = false, bool SP2 = false>
; __device__ __forceinline__ void gemm_phase(PG8_LAS unsigned char* lds, const Gemm g, const Sched& S, const Epi& E) {
;     ...
;             const char* a1 = cA + (size_t)(t + 1) * kstep;
;             const char* a2 = last ? nA : cA + (size_t)(t + 2) * kstep; const char* b2 = last ? nB : cB + (size_t)(t + 2) * kstep;
;             const char* a3 = a2 + kstep; const char* b3 = b2 + kstep;
;             if (last && has_next) S.a_ready(nxt);
;             if constexpr (SP2) {
;             PG8_LDB(B0, 0, 0); PG8_LDB(B1, 0, 1); PG8_SCHED; PG8_LDA(At, 0, 0); PG8_STAGE(PG8_SA(1, 1), a1 + hstep, voffA);
;             PG8_WAIT_V(8); PG8_WAIT_L(0); PG8_BAR; PG8_MMA(0, 0, At, B0); PG8_MMA(0, 1, At, B1); PG8_BAR; PG8_SCHED;
;             PG8_LDA(At, 0, 1); PG8_STAGE(PG8_SB(0, 0), b2, voffB); PG8_STAGE(PG8_SB(0, 1), b2 + hstep, voffB); PG8_STAGE(PG8_SA(0, 0), a2, voffA);
;     ...
;         for (int a = 0; a < 2; ++a)
; #pragma unroll
;             for (int b = 0; b < 2; ++b)
; #pragma unroll
;                 for (int m = 0; m < 4; ++m)
; #pragma unroll
;                     for (int n = 0; n < 2; ++n) acc[a][b][m][n] = (f32x4){0.f, 0.f, 0.f, 0.f};
.LBB0_224:
	s_ashr_i32 s15, s14, 31
	s_lshl_b64 s[16:17], s[14:15], 19
	s_add_u32 s16, s34, s16
	s_addc_u32 s17, s35, s17
	s_and_b64 s[18:19], s[2:3], exec
	s_cselect_b32 s5, s17, s23
	s_cselect_b32 s15, s16, s22
	s_ashr_i32 s13, s12, 31
	s_lshl_b64 s[18:19], s[12:13], 19
	s_add_u32 s18, s38, s18
	s_addc_u32 s19, s39, s19
	s_and_b64 s[26:27], s[2:3], exec
	s_cselect_b32 s13, s19, s25
	s_cselect_b32 s21, s18, s24
	s_add_u32 s22, s22, 0x40080
	s_addc_u32 s23, s23, 0
	s_add_u32 s49, s24, 0x100
	s_addc_u32 s50, s25, 0
	s_mov_b32 s51, -2
	s_add_u32 s24, s22, 0xfffc0080
	s_addc_u32 s25, s23, -1
	s_add_i32 s52, 0, 0x10000
	s_cmp_eq_u32 s51, 12
	s_cselect_b32 s27, s5, s25
	s_cselect_b32 s26, s15, s24
	v_add_u32_e32 v138, s52, v149
	s_cselect_b32 s25, s13, s50
	s_cselect_b32 s24, s21, s49
	s_add_i32 s55, 0, 0x14000
	ds_read_b128 v[144:147], v138
	ds_read_b128 v[154:157], v138 offset:1024
	ds_read_b128 v[158:161], v138 offset:2048
	ds_read_b128 v[162:165], v138 offset:3072
	v_add_u32_e32 v138, s55, v149
	ds_read_b128 v[166:169], v138
	ds_read_b128 v[170:173], v138 offset:1024
	ds_read_b128 v[174:177], v138 offset:2048
	ds_read_b128 v[178:181], v138 offset:3072
	v_lshl_add_u64 v[138:139], s[22:23], 0, v[136:137]
	s_add_i32 m0, s41, 0xc000
	ds_read_b128 v[182:185], v152
	ds_read_b128 v[186:189], v152 offset:1024
	ds_read_b128 v[190:193], v152 offset:2048
	ds_read_b128 v[194:197], v152 offset:3072
	ds_read_b128 v[198:201], v152 offset:4096
	ds_read_b128 v[202:205], v152 offset:5120
	ds_read_b128 v[224:227], v152 offset:6144
	ds_read_b128 v[228:231], v152 offset:7168
	global_load_lds_dwordx4 v[138:139], off
	v_lshl_add_u64 v[138:139], s[22:23], 0, v[142:143]
	s_add_i32 m0, s41, 0xe000
	s_nop 0
	global_load_lds_dwordx4 v[138:139], off
	s_waitcnt vmcnt(8)
	s_waitcnt lgkmcnt(0)
	s_barrier
	s_setprio 1
	s_waitcnt lgkmcnt(0)
	v_mfma_f32_16x16x32_bf16 v[126:129], v[144:147], v[182:185], 0
	v_mfma_f32_16x16x32_bf16 v[122:125], v[158:161], v[182:185], 0
	v_mfma_f32_16x16x32_bf16 v[110:113], v[144:147], v[190:193], 0
	v_mfma_f32_16x16x32_bf16 v[106:109], v[158:161], v[190:193], 0
	v_mfma_f32_16x16x32_bf16 v[94:97], v[144:147], v[198:201], 0
	v_mfma_f32_16x16x32_bf16 v[90:93], v[158:161], v[198:201], 0
	v_mfma_f32_16x16x32_bf16 v[78:81], v[144:147], v[224:227], 0
	v_mfma_f32_16x16x32_bf16 v[74:77], v[158:161], v[224:227], 0
	v_mfma_f32_16x16x32_bf16 v[126:129], v[154:157], v[186:189], v[126:129]
	v_mfma_f32_16x16x32_bf16 v[122:125], v[162:165], v[186:189], v[122:125]
	v_mfma_f32_16x16x32_bf16 v[110:113], v[154:157], v[194:197], v[110:113]
	v_mfma_f32_16x16x32_bf16 v[106:109], v[162:165], v[194:197], v[106:109]
	v_mfma_f32_16x16x32_bf16 v[94:97], v[154:157], v[202:205], v[94:97]
	v_mfma_f32_16x16x32_bf16 v[90:93], v[162:165], v[202:205], v[90:93]
	v_mfma_f32_16x16x32_bf16 v[78:81], v[154:157], v[228:231], v[78:81]
	v_mfma_f32_16x16x32_bf16 v[74:77], v[162:165], v[228:231], v[74:77]
	s_setprio 0
	s_setprio 1
	v_mfma_f32_16x16x32_bf16 v[118:121], v[166:169], v[182:185], 0
	v_mfma_f32_16x16x32_bf16 v[114:117], v[174:177], v[182:185], 0
	v_mfma_f32_16x16x32_bf16 v[102:105], v[166:169], v[190:193], 0
	v_mfma_f32_16x16x32_bf16 v[98:101], v[174:177], v[190:193], 0
	v_mfma_f32_16x16x32_bf16 v[86:89], v[166:169], v[198:201], 0
	v_mfma_f32_16x16x32_bf16 v[82:85], v[174:177], v[198:201], 0
	v_mfma_f32_16x16x32_bf16 v[70:73], v[166:169], v[224:227], 0
	v_mfma_f32_16x16x32_bf16 v[66:69], v[174:177], v[224:227], 0
	v_mfma_f32_16x16x32_bf16 v[118:121], v[170:173], v[186:189], v[118:121]
	v_mfma_f32_16x16x32_bf16 v[114:117], v[178:181], v[186:189], v[114:117]
	v_mfma_f32_16x16x32_bf16 v[102:105], v[170:173], v[194:197], v[102:105]
	v_mfma_f32_16x16x32_bf16 v[98:101], v[178:181], v[194:197], v[98:101]
	v_mfma_f32_16x16x32_bf16 v[86:89], v[170:173], v[202:205], v[86:89]
	v_mfma_f32_16x16x32_bf16 v[82:85], v[178:181], v[202:205], v[82:85]
	v_mfma_f32_16x16x32_bf16 v[70:73], v[170:173], v[228:231], v[70:73]
	v_mfma_f32_16x16x32_bf16 v[66:69], v[178:181], v[228:231], v[66:69]
	s_setprio 0
	s_barrier
	s_add_i32 s52, s52, s31
	v_lshl_add_u64 v[138:139], s[24:25], 0, v[0:1]
	s_mov_b32 m0, s52
	ds_read_b128 v[182:185], v152 offset:16384
	ds_read_b128 v[186:189], v152 offset:17408
	ds_read_b128 v[190:193], v152 offset:18432
	ds_read_b128 v[194:197], v152 offset:19456
	ds_read_b128 v[198:201], v152 offset:20480
	ds_read_b128 v[202:205], v152 offset:21504
	ds_read_b128 v[224:227], v152 offset:22528
	ds_read_b128 v[228:231], v152 offset:23552
	global_load_lds_dwordx4 v[138:139], off
	s_add_i32 m0, s52, 0x2000
	s_add_u32 s52, s24, 0x40000
	v_lshl_add_u64 v[140:141], s[24:25], 0, v[134:135]
	s_addc_u32 s53, s25, 0
	s_add_i32 s55, s55, s31
	global_load_lds_dwordx4 v[140:141], off
	v_lshl_add_u64 v[232:233], s[52:53], 0, v[0:1]
	s_mov_b32 m0, s55
	v_lshl_add_u64 v[234:235], s[26:27], 0, v[132:133]
	global_load_lds_dwordx4 v[232:233], off
	v_lshl_add_u64 v[232:233], s[52:53], 0, v[134:135]
	s_add_i32 m0, s55, 0x2000
	s_nop 0
	global_load_lds_dwordx4 v[232:233], off
	v_lshl_add_u64 v[232:233], s[26:27], 0, v[130:131]
	s_mov_b32 m0, s41
	s_nop 0
	global_load_lds_dwordx4 v[232:233], off
	s_mov_b32 m0, s42
	s_nop 0
	global_load_lds_dwordx4 v[234:235], off
	s_waitcnt vmcnt(8)
	s_waitcnt lgkmcnt(0)
	s_barrier
; #define PG8_STAGE(bufoff, gbase, voff) do { _Pragma("unroll") for (int _i = 0; _i < 2; ++_i) \
;         __builtin_amdgcn_global_load_lds((const unsigned*)((const char*)(gbase) + (voff)[_i]), (PG8_LAS unsigned*)(lds + (bufoff) + ldsw + _i * 8192), 16, 0, 0); } while (0)
; #define PG8_LDA(dst, b, h) do { _Pragma("unroll") for (int m = 0; m < 4; ++m) _Pragma("unroll") for (int k = 0; k < 2; ++k) dst[m][k] = *(const PG8_LAS bf16x8*)(lds + PG8_SA(b, h) + aoff + m * 2048 + k * 1024); } while (0)
; #define PG8_LDB(dst, b, h) do { _Pragma("unroll") for (int n = 0; n < 2; ++n) _Pragma("unroll") for (int k = 0; k < 2; ++k) dst[n][k] = *(const PG8_LAS bf16x8*)(lds + PG8_SB(b, h) + boff + n * 2048 + k * 1024); } while (0)
; #define PG8_MMA(ai, bj, At, Bt) do { __builtin_amdgcn_s_setprio(1); _Pragma("unroll") for (int m = 0; m < 4; ++m) _Pragma("unroll") for (int n = 0; n < 2; ++n) _Pragma("unroll") for (int k = 0; k < 2; ++k) \
;         acc[ai][bj][m][n] = __builtin_amdgcn_mfma_f32_16x16x32_bf16(Bt[n][k], At[m][k], acc[ai][bj][m][n], 0, 0, 0); __builtin_amdgcn_s_setprio(0); } while (0)
; #define PG8_WAIT_V(n) asm volatile("s_waitcnt vmcnt(" #n ")" ::: "memory")
; #define PG8_WAIT_L(n) asm volatile("s_waitcnt lgkmcnt(" #n ")" ::: "memory")
; #define PG8_BAR __builtin_amdgcn_s_barrier()
; #define PG8_SCHED __builtin_amdgcn_sched_barrier(0)
; template <class Epi, class Sched, bool ALIGN_EPI = false, bool SP2 = false>
; __device__ __forceinline__ void gemm_phase(PG8_LAS unsigned char* lds, const Gemm g, const Sched& S, const Epi& E) {
;     ...
;             PG8_WAIT_V(8); PG8_WAIT_L(0); PG8_BAR; PG8_MMA(1, 0, At, B0); PG8_MMA(1, 1, At, B1); PG8_BAR; PG8_SCHED;
;             PG8_LDB(B0, 1, 0); PG8_LDB(B1, 1, 1); PG8_SCHED; PG8_LDA(At, 1, 0); PG8_STAGE(PG8_SA(0, 1), a2 + hstep, voffA);
;             PG8_WAIT_V(8); PG8_WAIT_L(0); PG8_BAR; PG8_MMA(0, 0, At, B0); PG8_MMA(0, 1, At, B1); PG8_BAR; PG8_SCHED;
	s_setprio 1
	s_waitcnt lgkmcnt(0)
	v_mfma_f32_16x16x32_bf16 v[62:65], v[144:147], v[182:185], 0
	v_mfma_f32_16x16x32_bf16 v[58:61], v[158:161], v[182:185], 0
	v_mfma_f32_16x16x32_bf16 v[46:49], v[144:147], v[190:193], 0
	v_mfma_f32_16x16x32_bf16 v[42:45], v[158:161], v[190:193], 0
	v_mfma_f32_16x16x32_bf16 v[30:33], v[144:147], v[198:201], 0
	v_mfma_f32_16x16x32_bf16 v[26:29], v[158:161], v[198:201], 0
	v_mfma_f32_16x16x32_bf16 v[14:17], v[144:147], v[224:227], 0
	v_mfma_f32_16x16x32_bf16 v[10:13], v[158:161], v[224:227], 0
	v_mfma_f32_16x16x32_bf16 v[62:65], v[154:157], v[186:189], v[62:65]
	v_mfma_f32_16x16x32_bf16 v[58:61], v[162:165], v[186:189], v[58:61]
	v_mfma_f32_16x16x32_bf16 v[46:49], v[154:157], v[194:197], v[46:49]
	v_mfma_f32_16x16x32_bf16 v[42:45], v[162:165], v[194:197], v[42:45]
	v_mfma_f32_16x16x32_bf16 v[30:33], v[154:157], v[202:205], v[30:33]
	v_mfma_f32_16x16x32_bf16 v[26:29], v[162:165], v[202:205], v[26:29]
	v_mfma_f32_16x16x32_bf16 v[14:17], v[154:157], v[228:231], v[14:17]
	v_mfma_f32_16x16x32_bf16 v[10:13], v[162:165], v[228:231], v[10:13]
	s_setprio 0
	s_setprio 1
	v_mfma_f32_16x16x32_bf16 v[54:57], v[166:169], v[182:185], 0
	v_mfma_f32_16x16x32_bf16 v[50:53], v[174:177], v[182:185], 0
	v_mfma_f32_16x16x32_bf16 v[38:41], v[166:169], v[190:193], 0
	v_mfma_f32_16x16x32_bf16 v[34:37], v[174:177], v[190:193], 0
	v_mfma_f32_16x16x32_bf16 v[22:25], v[166:169], v[198:201], 0
	v_mfma_f32_16x16x32_bf16 v[18:21], v[174:177], v[198:201], 0
	v_mfma_f32_16x16x32_bf16 v[6:9], v[166:169], v[224:227], 0
	v_mfma_f32_16x16x32_bf16 v[2:5], v[174:177], v[224:227], 0
	v_mfma_f32_16x16x32_bf16 v[54:57], v[170:173], v[186:189], v[54:57]
	v_mfma_f32_16x16x32_bf16 v[50:53], v[178:181], v[186:189], v[50:53]
	v_mfma_f32_16x16x32_bf16 v[38:41], v[170:173], v[194:197], v[38:41]
	v_mfma_f32_16x16x32_bf16 v[34:37], v[178:181], v[194:197], v[34:37]
	v_mfma_f32_16x16x32_bf16 v[22:25], v[170:173], v[202:205], v[22:25]
	v_mfma_f32_16x16x32_bf16 v[18:21], v[178:181], v[202:205], v[18:21]
	v_mfma_f32_16x16x32_bf16 v[6:9], v[170:173], v[228:231], v[6:9]
	v_mfma_f32_16x16x32_bf16 v[2:5], v[178:181], v[228:231], v[2:5]
	s_setprio 0
	s_barrier
	s_add_i32 s52, 0, 0x18000
	v_add_u32_e32 v153, s52, v149
	s_add_i32 s53, 0, 0x1c000
	ds_read_b128 v[144:147], v153
	ds_read_b128 v[154:157], v153 offset:1024
	ds_read_b128 v[158:161], v153 offset:2048
	ds_read_b128 v[162:165], v153 offset:3072
	v_add_u32_e32 v153, s53, v149
	ds_read_b128 v[166:169], v153
	ds_read_b128 v[170:173], v153 offset:1024
	ds_read_b128 v[174:177], v153 offset:2048
	ds_read_b128 v[178:181], v153 offset:3072
	s_add_u32 s26, s26, 0x40000
	s_addc_u32 s27, s27, 0
	s_mov_b32 m0, s43
	v_lshl_add_u64 v[236:237], s[26:27], 0, v[130:131]
	ds_read_b128 v[182:185], v152 offset:32768
	ds_read_b128 v[186:189], v152 offset:33792
	ds_read_b128 v[190:193], v152 offset:34816
	ds_read_b128 v[194:197], v152 offset:35840
	ds_read_b128 v[198:201], v152 offset:36864
	ds_read_b128 v[202:205], v152 offset:37888
	ds_read_b128 v[224:227], v152 offset:38912
	ds_read_b128 v[228:231], v152 offset:39936
	global_load_lds_dwordx4 v[236:237], off
	v_lshl_add_u64 v[236:237], s[26:27], 0, v[132:133]
	s_mov_b32 m0, s44
	s_nop 0
	global_load_lds_dwordx4 v[236:237], off
	s_waitcnt vmcnt(8)
	s_waitcnt lgkmcnt(0)
	s_barrier
	s_setprio 1
	s_waitcnt lgkmcnt(0)
	v_mfma_f32_16x16x32_bf16 v[126:129], v[144:147], v[182:185], v[126:129]
	v_mfma_f32_16x16x32_bf16 v[122:125], v[158:161], v[182:185], v[122:125]
	v_mfma_f32_16x16x32_bf16 v[110:113], v[144:147], v[190:193], v[110:113]
	v_mfma_f32_16x16x32_bf16 v[106:109], v[158:161], v[190:193], v[106:109]
	v_mfma_f32_16x16x32_bf16 v[94:97], v[144:147], v[198:201], v[94:97]
	v_mfma_f32_16x16x32_bf16 v[90:93], v[158:161], v[198:201], v[90:93]
	v_mfma_f32_16x16x32_bf16 v[78:81], v[144:147], v[224:227], v[78:81]
	v_mfma_f32_16x16x32_bf16 v[74:77], v[158:161], v[224:227], v[74:77]
	v_mfma_f32_16x16x32_bf16 v[126:129], v[154:157], v[186:189], v[126:129]
	v_mfma_f32_16x16x32_bf16 v[122:125], v[162:165], v[186:189], v[122:125]
	v_mfma_f32_16x16x32_bf16 v[110:113], v[154:157], v[194:197], v[110:113]
	v_mfma_f32_16x16x32_bf16 v[106:109], v[162:165], v[194:197], v[106:109]
	v_mfma_f32_16x16x32_bf16 v[94:97], v[154:157], v[202:205], v[94:97]
	v_mfma_f32_16x16x32_bf16 v[90:93], v[162:165], v[202:205], v[90:93]
	v_mfma_f32_16x16x32_bf16 v[78:81], v[154:157], v[228:231], v[78:81]
	v_mfma_f32_16x16x32_bf16 v[74:77], v[162:165], v[228:231], v[74:77]
	s_setprio 0
	s_setprio 1
	v_mfma_f32_16x16x32_bf16 v[118:121], v[166:169], v[182:185], v[118:121]
	v_mfma_f32_16x16x32_bf16 v[114:117], v[174:177], v[182:185], v[114:117]
	v_mfma_f32_16x16x32_bf16 v[102:105], v[166:169], v[190:193], v[102:105]
	v_mfma_f32_16x16x32_bf16 v[98:101], v[174:177], v[190:193], v[98:101]
	v_mfma_f32_16x16x32_bf16 v[86:89], v[166:169], v[198:201], v[86:89]
	v_mfma_f32_16x16x32_bf16 v[82:85], v[174:177], v[198:201], v[82:85]
	v_mfma_f32_16x16x32_bf16 v[70:73], v[166:169], v[224:227], v[70:73]
	v_mfma_f32_16x16x32_bf16 v[66:69], v[174:177], v[224:227], v[66:69]
	v_mfma_f32_16x16x32_bf16 v[118:121], v[170:173], v[186:189], v[118:121]
	v_mfma_f32_16x16x32_bf16 v[114:117], v[178:181], v[186:189], v[114:117]
	v_mfma_f32_16x16x32_bf16 v[102:105], v[170:173], v[194:197], v[102:105]
	v_mfma_f32_16x16x32_bf16 v[98:101], v[178:181], v[194:197], v[98:101]
	v_mfma_f32_16x16x32_bf16 v[86:89], v[170:173], v[202:205], v[86:89]
	v_mfma_f32_16x16x32_bf16 v[82:85], v[178:181], v[202:205], v[82:85]
	v_mfma_f32_16x16x32_bf16 v[70:73], v[170:173], v[228:231], v[70:73]
	v_mfma_f32_16x16x32_bf16 v[66:69], v[178:181], v[228:231], v[66:69]
	s_setprio 0
	s_barrier
; #define PG8_STAGE(bufoff, gbase, voff) do { _Pragma("unroll") for (int _i = 0; _i < 2; ++_i) \
;         __builtin_amdgcn_global_load_lds((const unsigned*)((const char*)(gbase) + (voff)[_i]), (PG8_LAS unsigned*)(lds + (bufoff) + ldsw + _i * 8192), 16, 0, 0); } while (0)
; #define PG8_LDA(dst, b, h) do { _Pragma("unroll") for (int m = 0; m < 4; ++m) _Pragma("unroll") for (int k = 0; k < 2; ++k) dst[m][k] = *(const PG8_LAS bf16x8*)(lds + PG8_SA(b, h) + aoff + m * 2048 + k * 1024); } while (0)
; #define PG8_MMA(ai, bj, At, Bt) do { __builtin_amdgcn_s_setprio(1); _Pragma("unroll") for (int m = 0; m < 4; ++m) _Pragma("unroll") for (int n = 0; n < 2; ++n) _Pragma("unroll") for (int k = 0; k < 2; ++k) \
;         acc[ai][bj][m][n] = __builtin_amdgcn_mfma_f32_16x16x32_bf16(Bt[n][k], At[m][k], acc[ai][bj][m][n], 0, 0, 0); __builtin_amdgcn_s_setprio(0); } while (0)
; #define PG8_WAIT_V(n) asm volatile("s_waitcnt vmcnt(" #n ")" ::: "memory")
; #define PG8_WAIT_L(n) asm volatile("s_waitcnt lgkmcnt(" #n ")" ::: "memory")
; #define PG8_BAR __builtin_amdgcn_s_barrier()
; #define PG8_SCHED __builtin_amdgcn_sched_barrier(0)
; template <class Epi, class Sched, bool ALIGN_EPI = false, bool SP2 = false>
; __device__ __forceinline__ void gemm_phase(PG8_LAS unsigned char* lds, const Gemm g, const Sched& S, const Epi& E) {
;     ...
;             PG8_LDA(At, 1, 1); PG8_STAGE(PG8_SB(1, 0), b3, voffB); PG8_STAGE(PG8_SB(1, 1), b3 + hstep, voffB); PG8_STAGE(PG8_SA(1, 0), a3, voffA);
;             PG8_WAIT_V(8); PG8_WAIT_L(0); PG8_BAR; PG8_MMA(1, 0, At, B0); PG8_MMA(1, 1, At, B1); PG8_BAR; PG8_SCHED;
	s_add_i32 s26, s52, s31
	v_lshl_add_u64 v[138:139], v[138:139], 0, s[86:87]
	s_mov_b32 m0, s26
	ds_read_b128 v[182:185], v152 offset:49152
	ds_read_b128 v[186:189], v152 offset:50176
	ds_read_b128 v[190:193], v152 offset:51200
	ds_read_b128 v[194:197], v152 offset:52224
	ds_read_b128 v[198:201], v152 offset:53248
	ds_read_b128 v[202:205], v152 offset:54272
	ds_read_b128 v[224:227], v152 offset:55296
	ds_read_b128 v[228:231], v152 offset:56320
	global_load_lds_dwordx4 v[138:139], off
	s_add_i32 m0, s26, 0x2000
	s_add_u32 s24, s24, 0x40080
	v_lshl_add_u64 v[138:139], v[140:141], 0, s[86:87]
	s_addc_u32 s25, s25, 0
	s_add_i32 s26, s53, s31
	global_load_lds_dwordx4 v[138:139], off
	v_lshl_add_u64 v[138:139], s[24:25], 0, v[0:1]
	s_mov_b32 m0, s26
	s_nop 0
	global_load_lds_dwordx4 v[138:139], off
	v_lshl_add_u64 v[138:139], s[24:25], 0, v[134:135]
	s_add_i32 m0, s26, 0x2000
	s_nop 0
	global_load_lds_dwordx4 v[138:139], off
	v_lshl_add_u64 v[138:139], v[232:233], 0, s[86:87]
	s_mov_b32 m0, s45
	s_nop 0
	global_load_lds_dwordx4 v[138:139], off
	v_lshl_add_u64 v[138:139], v[234:235], 0, s[86:87]
	s_mov_b32 m0, s46
	s_nop 0
	global_load_lds_dwordx4 v[138:139], off
	s_waitcnt vmcnt(8)
	s_waitcnt lgkmcnt(0)
	s_barrier
	s_setprio 1
	s_waitcnt lgkmcnt(0)
	v_mfma_f32_16x16x32_bf16 v[62:65], v[144:147], v[182:185], v[62:65]
	v_mfma_f32_16x16x32_bf16 v[58:61], v[158:161], v[182:185], v[58:61]
	v_mfma_f32_16x16x32_bf16 v[46:49], v[144:147], v[190:193], v[46:49]
	v_mfma_f32_16x16x32_bf16 v[42:45], v[158:161], v[190:193], v[42:45]
	v_mfma_f32_16x16x32_bf16 v[30:33], v[144:147], v[198:201], v[30:33]
	v_mfma_f32_16x16x32_bf16 v[26:29], v[158:161], v[198:201], v[26:29]
	v_mfma_f32_16x16x32_bf16 v[14:17], v[144:147], v[224:227], v[14:17]
	v_mfma_f32_16x16x32_bf16 v[10:13], v[158:161], v[224:227], v[10:13]
	v_mfma_f32_16x16x32_bf16 v[62:65], v[154:157], v[186:189], v[62:65]
	v_mfma_f32_16x16x32_bf16 v[58:61], v[162:165], v[186:189], v[58:61]
	v_mfma_f32_16x16x32_bf16 v[46:49], v[154:157], v[194:197], v[46:49]
	v_mfma_f32_16x16x32_bf16 v[42:45], v[162:165], v[194:197], v[42:45]
	v_mfma_f32_16x16x32_bf16 v[30:33], v[154:157], v[202:205], v[30:33]
	v_mfma_f32_16x16x32_bf16 v[26:29], v[162:165], v[202:205], v[26:29]
	v_mfma_f32_16x16x32_bf16 v[14:17], v[154:157], v[228:231], v[14:17]
	v_mfma_f32_16x16x32_bf16 v[10:13], v[162:165], v[228:231], v[10:13]
	s_setprio 0
	s_setprio 1
	v_mfma_f32_16x16x32_bf16 v[54:57], v[166:169], v[182:185], v[54:57]
	v_mfma_f32_16x16x32_bf16 v[50:53], v[174:177], v[182:185], v[50:53]
	v_mfma_f32_16x16x32_bf16 v[38:41], v[166:169], v[190:193], v[38:41]
	v_mfma_f32_16x16x32_bf16 v[34:37], v[174:177], v[190:193], v[34:37]
	v_mfma_f32_16x16x32_bf16 v[22:25], v[166:169], v[198:201], v[22:25]
	v_mfma_f32_16x16x32_bf16 v[18:21], v[174:177], v[198:201], v[18:21]
	v_mfma_f32_16x16x32_bf16 v[6:9], v[166:169], v[224:227], v[6:9]
	v_mfma_f32_16x16x32_bf16 v[2:5], v[174:177], v[224:227], v[2:5]
	v_mfma_f32_16x16x32_bf16 v[54:57], v[170:173], v[186:189], v[54:57]
	v_mfma_f32_16x16x32_bf16 v[50:53], v[178:181], v[186:189], v[50:53]
	v_mfma_f32_16x16x32_bf16 v[38:41], v[170:173], v[194:197], v[38:41]
	v_mfma_f32_16x16x32_bf16 v[34:37], v[178:181], v[194:197], v[34:37]
	v_mfma_f32_16x16x32_bf16 v[22:25], v[170:173], v[202:205], v[22:25]
	v_mfma_f32_16x16x32_bf16 v[18:21], v[178:181], v[202:205], v[18:21]
	v_mfma_f32_16x16x32_bf16 v[6:9], v[170:173], v[228:231], v[6:9]
	v_mfma_f32_16x16x32_bf16 v[2:5], v[178:181], v[228:231], v[2:5]
	s_setprio 0
	s_barrier
	s_add_i32 s51, s51, 2
	s_add_u32 s22, s22, 0x100
	s_addc_u32 s23, s23, 0
	s_add_u32 s49, s49, 0x100
	s_addc_u32 s50, s50, 0
	s_cmp_gt_u32 s51, 13
	s_cbranch_scc1 .Lpeel_exit_sw

; #define PG8_BAR __builtin_amdgcn_s_barrier()
; template <class Epi, class Sched, bool ALIGN_EPI = false, bool SP2 = false>
; __device__ __forceinline__ void gemm_phase(PG8_LAS unsigned char* lds, const Gemm g, const Sched& S, const Epi& E) {
;     ...
;         if constexpr (ALIGN_EPI) { if (wr == 0) PG8_BAR; }
;     __device__ __forceinline__ void operator()(const f32x4 (&acc)[2][2][4][2], const Unit& u, int wr, int wc, int fr, int fq) const {
;     ...
;                 const int row = row0 + ai * 128 + m * 16; const float rs = (u.pm == pm0) ? RS[row & 255] : row_rstd(ss, row), rsl = -LOG2E_ * rs, rs2 = rs * rs;
.Lpeel_exit_sw:
	ds_read_b32 v224, v150
	ds_read_b32 v225, v150 offset:64
	ds_read_b32 v226, v150 offset:128
	ds_read_b32 v227, v150 offset:192
	ds_read_b32 v228, v150 offset:512
	ds_read_b32 v229, v150 offset:576
	ds_read_b32 v230, v150 offset:640
	ds_read_b32 v231, v150 offset:704
	s_and_b64 vcc, exec, s[10:11]
	s_cbranch_vccz .LBB0_228
	s_barrier

; #define PG8_STAGE(bufoff, gbase, voff) do { _Pragma("unroll") for (int _i = 0; _i < 2; ++_i) \
;         __builtin_amdgcn_global_load_lds((const unsigned*)((const char*)(gbase) + (voff)[_i]), (PG8_LAS unsigned*)(lds + (bufoff) + ldsw + _i * 8192), 16, 0, 0); } while (0)
; #define PG8_LDA(dst, b, h) do { _Pragma("unroll") for (int m = 0; m < 4; ++m) _Pragma("unroll") for (int k = 0; k < 2; ++k) dst[m][k] = *(const PG8_LAS bf16x8*)(lds + PG8_SA(b, h) + aoff + m * 2048 + k * 1024); } while (0)
; #define PG8_LDB(dst, b, h) do { _Pragma("unroll") for (int n = 0; n < 2; ++n) _Pragma("unroll") for (int k = 0; k < 2; ++k) dst[n][k] = *(const PG8_LAS bf16x8*)(lds + PG8_SB(b, h) + boff + n * 2048 + k * 1024); } while (0)
; #define PG8_MMA(ai, bj, At, Bt) do { __builtin_amdgcn_s_setprio(1); _Pragma("unroll") for (int m = 0; m < 4; ++m) _Pragma("unroll") for (int n = 0; n < 2; ++n) _Pragma("unroll") for (int k = 0; k < 2; ++k) \
;         acc[ai][bj][m][n] = __builtin_amdgcn_mfma_f32_16x16x32_bf16(Bt[n][k], At[m][k], acc[ai][bj][m][n], 0, 0, 0); __builtin_amdgcn_s_setprio(0); } while (0)
; #define PG8_WAIT_V(n) asm volatile("s_waitcnt vmcnt(" #n ")" ::: "memory")
; template <class Epi, class Sched, bool ALIGN_EPI = false, bool SP2 = false>
; __device__ __forceinline__ void gemm_phase(PG8_LAS unsigned char* lds, const Gemm g, const Sched& S, const Epi& E) {
;     ...
;             const char* a1 = cA + (size_t)(t + 1) * kstep;
;             const char* a2 = last ? nA : cA + (size_t)(t + 2) * kstep; const char* b2 = last ? nB : cB + (size_t)(t + 2) * kstep;
;             const char* a3 = a2 + kstep; const char* b3 = b2 + kstep;
;             if (last && has_next) S.a_ready(nxt);
;             if constexpr (SP2) {
;             PG8_LDB(B0, 0, 0); PG8_LDB(B1, 0, 1); PG8_SCHED; PG8_LDA(At, 0, 0); PG8_STAGE(PG8_SA(1, 1), a1 + hstep, voffA);
;             PG8_WAIT_V(8); PG8_WAIT_L(0); PG8_BAR; PG8_MMA(0, 0, At, B0); PG8_MMA(0, 1, At, B1); PG8_BAR; PG8_SCHED;
;             PG8_LDA(At, 0, 1); PG8_STAGE(PG8_SB(0, 0), b2, voffB); PG8_STAGE(PG8_SB(0, 1), b2 + hstep, voffB); PG8_STAGE(PG8_SA(0, 0), a2, voffA);
;     ...
;         for (int a = 0; a < 2; ++a)
; #pragma unroll
;             for (int b = 0; b < 2; ++b)
; #pragma unroll
;                 for (int m = 0; m < 4; ++m)
; #pragma unroll
;                     for (int n = 0; n < 2; ++n) acc[a][b][m][n] = (f32x4){0.f, 0.f, 0.f, 0.f};
.LBB0_491:
	s_ashr_i32 s15, s14, 31
	s_lshl_b64 s[16:17], s[14:15], 19
	s_add_u32 s16, s34, s16
	s_addc_u32 s17, s35, s17
	s_and_b64 s[18:19], s[2:3], exec
	s_cselect_b32 s5, s17, s9
	s_cselect_b32 s7, s16, s8
	s_ashr_i32 s13, s12, 31
	s_lshl_b64 s[18:19], s[12:13], 19
	s_add_u32 s18, s27, s18
	s_addc_u32 s19, s29, s19
	s_and_b64 s[22:23], s[2:3], exec
	s_cselect_b32 s13, s19, s21
	s_cselect_b32 s15, s18, s20
	s_add_u32 s8, s8, 0x40080
	s_addc_u32 s9, s9, 0
	s_add_u32 s45, s20, 0x100
	s_addc_u32 s46, s21, 0
	s_mov_b32 s47, -2
	s_add_u32 s20, s8, 0xfffc0080
	s_addc_u32 s21, s9, -1
	s_add_i32 s48, 0, 0x10000
	s_cmp_eq_u32 s47, 12
	s_cselect_b32 s23, s5, s21
	s_cselect_b32 s22, s7, s20
	v_add_u32_e32 v138, s48, v161
	s_cselect_b32 s21, s13, s46
	s_cselect_b32 s20, s15, s45
	s_add_i32 s50, 0, 0x14000
	ds_read_b128 v[144:147], v138
	ds_read_b128 v[148:151], v138 offset:1024
	ds_read_b128 v[152:155], v138 offset:2048
	ds_read_b128 v[156:159], v138 offset:3072
	v_add_u32_e32 v138, s50, v161
	ds_read_b128 v[166:169], v138
	ds_read_b128 v[170:173], v138 offset:1024
	ds_read_b128 v[174:177], v138 offset:2048
	ds_read_b128 v[178:181], v138 offset:3072
	v_lshl_add_u64 v[138:139], s[8:9], 0, v[136:137]
	s_add_i32 m0, s30, 0xc000
	ds_read_b128 v[182:185], v164
	ds_read_b128 v[186:189], v164 offset:1024
	ds_read_b128 v[190:193], v164 offset:2048
	ds_read_b128 v[194:197], v164 offset:3072
	ds_read_b128 v[198:201], v164 offset:4096
	ds_read_b128 v[202:205], v164 offset:5120
	ds_read_b128 v[224:227], v164 offset:6144
	ds_read_b128 v[228:231], v164 offset:7168
	global_load_lds_dwordx4 v[138:139], off
	v_lshl_add_u64 v[138:139], s[8:9], 0, v[142:143]
	s_add_i32 m0, s30, 0xe000
	s_nop 0
	global_load_lds_dwordx4 v[138:139], off
	s_waitcnt vmcnt(8)
	s_waitcnt lgkmcnt(0)
	s_barrier
	s_setprio 1
	s_waitcnt lgkmcnt(0)
	v_mfma_f32_16x16x32_bf16 v[126:129], v[144:147], v[182:185], 0
	v_mfma_f32_16x16x32_bf16 v[122:125], v[152:155], v[182:185], 0
	v_mfma_f32_16x16x32_bf16 v[110:113], v[144:147], v[190:193], 0
	v_mfma_f32_16x16x32_bf16 v[106:109], v[152:155], v[190:193], 0
	v_mfma_f32_16x16x32_bf16 v[94:97], v[144:147], v[198:201], 0
	v_mfma_f32_16x16x32_bf16 v[90:93], v[152:155], v[198:201], 0
	v_mfma_f32_16x16x32_bf16 v[78:81], v[144:147], v[224:227], 0
	v_mfma_f32_16x16x32_bf16 v[74:77], v[152:155], v[224:227], 0
	v_mfma_f32_16x16x32_bf16 v[126:129], v[148:151], v[186:189], v[126:129]
	v_mfma_f32_16x16x32_bf16 v[122:125], v[156:159], v[186:189], v[122:125]
	v_mfma_f32_16x16x32_bf16 v[110:113], v[148:151], v[194:197], v[110:113]
	v_mfma_f32_16x16x32_bf16 v[106:109], v[156:159], v[194:197], v[106:109]
	v_mfma_f32_16x16x32_bf16 v[94:97], v[148:151], v[202:205], v[94:97]
	v_mfma_f32_16x16x32_bf16 v[90:93], v[156:159], v[202:205], v[90:93]
	v_mfma_f32_16x16x32_bf16 v[78:81], v[148:151], v[228:231], v[78:81]
	v_mfma_f32_16x16x32_bf16 v[74:77], v[156:159], v[228:231], v[74:77]
	s_setprio 0
	s_setprio 1
	v_mfma_f32_16x16x32_bf16 v[118:121], v[166:169], v[182:185], 0
	v_mfma_f32_16x16x32_bf16 v[114:117], v[174:177], v[182:185], 0
	v_mfma_f32_16x16x32_bf16 v[102:105], v[166:169], v[190:193], 0
	v_mfma_f32_16x16x32_bf16 v[98:101], v[174:177], v[190:193], 0
	v_mfma_f32_16x16x32_bf16 v[86:89], v[166:169], v[198:201], 0
	v_mfma_f32_16x16x32_bf16 v[82:85], v[174:177], v[198:201], 0
	v_mfma_f32_16x16x32_bf16 v[70:73], v[166:169], v[224:227], 0
	v_mfma_f32_16x16x32_bf16 v[66:69], v[174:177], v[224:227], 0
	v_mfma_f32_16x16x32_bf16 v[118:121], v[170:173], v[186:189], v[118:121]
	v_mfma_f32_16x16x32_bf16 v[114:117], v[178:181], v[186:189], v[114:117]
	v_mfma_f32_16x16x32_bf16 v[102:105], v[170:173], v[194:197], v[102:105]
	v_mfma_f32_16x16x32_bf16 v[98:101], v[178:181], v[194:197], v[98:101]
	v_mfma_f32_16x16x32_bf16 v[86:89], v[170:173], v[202:205], v[86:89]
	v_mfma_f32_16x16x32_bf16 v[82:85], v[178:181], v[202:205], v[82:85]
	v_mfma_f32_16x16x32_bf16 v[70:73], v[170:173], v[228:231], v[70:73]
	v_mfma_f32_16x16x32_bf16 v[66:69], v[178:181], v[228:231], v[66:69]
	s_setprio 0
	s_barrier
	s_add_i32 s48, s48, s26
	v_lshl_add_u64 v[138:139], s[20:21], 0, v[0:1]
	s_mov_b32 m0, s48
	ds_read_b128 v[182:185], v164 offset:16384
	ds_read_b128 v[186:189], v164 offset:17408
	ds_read_b128 v[190:193], v164 offset:18432
	ds_read_b128 v[194:197], v164 offset:19456
	ds_read_b128 v[198:201], v164 offset:20480
	ds_read_b128 v[202:205], v164 offset:21504
	ds_read_b128 v[224:227], v164 offset:22528
	ds_read_b128 v[228:231], v164 offset:23552
	global_load_lds_dwordx4 v[138:139], off
	s_add_i32 m0, s48, 0x2000
	s_add_u32 s48, s20, 0x40000
	v_lshl_add_u64 v[140:141], s[20:21], 0, v[134:135]
	s_addc_u32 s49, s21, 0
	s_add_i32 s50, s50, s26
	global_load_lds_dwordx4 v[140:141], off
	v_lshl_add_u64 v[232:233], s[48:49], 0, v[0:1]
	s_mov_b32 m0, s50
	v_lshl_add_u64 v[234:235], s[22:23], 0, v[132:133]
	global_load_lds_dwordx4 v[232:233], off
	v_lshl_add_u64 v[232:233], s[48:49], 0, v[134:135]
	s_add_i32 m0, s50, 0x2000
	s_nop 0
	global_load_lds_dwordx4 v[232:233], off
	v_lshl_add_u64 v[232:233], s[22:23], 0, v[130:131]
	s_mov_b32 m0, s30
	s_nop 0
	global_load_lds_dwordx4 v[232:233], off
	s_mov_b32 m0, s31
	s_nop 0
	global_load_lds_dwordx4 v[234:235], off
	s_waitcnt vmcnt(8)
	s_waitcnt lgkmcnt(0)
	s_barrier
; #define PG8_STAGE(bufoff, gbase, voff) do { _Pragma("unroll") for (int _i = 0; _i < 2; ++_i) \
;         __builtin_amdgcn_global_load_lds((const unsigned*)((const char*)(gbase) + (voff)[_i]), (PG8_LAS unsigned*)(lds + (bufoff) + ldsw + _i * 8192), 16, 0, 0); } while (0)
; #define PG8_LDA(dst, b, h) do { _Pragma("unroll") for (int m = 0; m < 4; ++m) _Pragma("unroll") for (int k = 0; k < 2; ++k) dst[m][k] = *(const PG8_LAS bf16x8*)(lds + PG8_SA(b, h) + aoff + m * 2048 + k * 1024); } while (0)
; #define PG8_LDB(dst, b, h) do { _Pragma("unroll") for (int n = 0; n < 2; ++n) _Pragma("unroll") for (int k = 0; k < 2; ++k) dst[n][k] = *(const PG8_LAS bf16x8*)(lds + PG8_SB(b, h) + boff + n * 2048 + k * 1024); } while (0)
; #define PG8_MMA(ai, bj, At, Bt) do { __builtin_amdgcn_s_setprio(1); _Pragma("unroll") for (int m = 0; m < 4; ++m) _Pragma("unroll") for (int n = 0; n < 2; ++n) _Pragma("unroll") for (int k = 0; k < 2; ++k) \
;         acc[ai][bj][m][n] = __builtin_amdgcn_mfma_f32_16x16x32_bf16(Bt[n][k], At[m][k], acc[ai][bj][m][n], 0, 0, 0); __builtin_amdgcn_s_setprio(0); } while (0)
; #define PG8_WAIT_V(n) asm volatile("s_waitcnt vmcnt(" #n ")" ::: "memory")
; template <class Epi, class Sched, bool ALIGN_EPI = false, bool SP2 = false>
; __device__ __forceinline__ void gemm_phase(PG8_LAS unsigned char* lds, const Gemm g, const Sched& S, const Epi& E) {
;     ...
;             PG8_LDB(B0, 0, 0); PG8_LDB(B1, 0, 1); PG8_SCHED; PG8_LDA(At, 0, 0); PG8_STAGE(PG8_SA(1, 1), a1 + hstep, voffA);
;             PG8_WAIT_V(8); PG8_WAIT_L(0); PG8_BAR; PG8_MMA(0, 0, At, B0); PG8_MMA(0, 1, At, B1); PG8_BAR; PG8_SCHED;
;             PG8_LDA(At, 0, 1); PG8_STAGE(PG8_SB(0, 0), b2, voffB); PG8_STAGE(PG8_SB(0, 1), b2 + hstep, voffB); PG8_STAGE(PG8_SA(0, 0), a2, voffA);
;             PG8_WAIT_V(8); PG8_WAIT_L(0); PG8_BAR; PG8_MMA(1, 0, At, B0); PG8_MMA(1, 1, At, B1); PG8_BAR; PG8_SCHED;
;             PG8_LDB(B0, 1, 0); PG8_LDB(B1, 1, 1); PG8_SCHED; PG8_LDA(At, 1, 0); PG8_STAGE(PG8_SA(0, 1), a2 + hstep, voffA);
;             PG8_WAIT_V(8); PG8_WAIT_L(0); PG8_BAR; PG8_MMA(0, 0, At, B0); PG8_MMA(0, 1, At, B1); PG8_BAR; PG8_SCHED;
;             PG8_LDA(At, 1, 1); PG8_STAGE(PG8_SB(1, 0), b3, voffB); PG8_STAGE(PG8_SB(1, 1), b3 + hstep, voffB); PG8_STAGE(PG8_SA(1, 0), a3, voffA);
;             PG8_WAIT_V(8); PG8_WAIT_L(0); PG8_BAR; PG8_MMA(1, 0, At, B0); PG8_MMA(1, 1, At, B1); PG8_BAR; PG8_SCHED;
	s_setprio 1
	s_waitcnt lgkmcnt(0)
	v_mfma_f32_16x16x32_bf16 v[62:65], v[144:147], v[182:185], 0
	v_mfma_f32_16x16x32_bf16 v[58:61], v[152:155], v[182:185], 0
	v_mfma_f32_16x16x32_bf16 v[46:49], v[144:147], v[190:193], 0
	v_mfma_f32_16x16x32_bf16 v[42:45], v[152:155], v[190:193], 0
	v_mfma_f32_16x16x32_bf16 v[30:33], v[144:147], v[198:201], 0
	v_mfma_f32_16x16x32_bf16 v[26:29], v[152:155], v[198:201], 0
	v_mfma_f32_16x16x32_bf16 v[14:17], v[144:147], v[224:227], 0
	v_mfma_f32_16x16x32_bf16 v[10:13], v[152:155], v[224:227], 0
	v_mfma_f32_16x16x32_bf16 v[62:65], v[148:151], v[186:189], v[62:65]
	v_mfma_f32_16x16x32_bf16 v[58:61], v[156:159], v[186:189], v[58:61]
	v_mfma_f32_16x16x32_bf16 v[46:49], v[148:151], v[194:197], v[46:49]
	v_mfma_f32_16x16x32_bf16 v[42:45], v[156:159], v[194:197], v[42:45]
	v_mfma_f32_16x16x32_bf16 v[30:33], v[148:151], v[202:205], v[30:33]
	v_mfma_f32_16x16x32_bf16 v[26:29], v[156:159], v[202:205], v[26:29]
	v_mfma_f32_16x16x32_bf16 v[14:17], v[148:151], v[228:231], v[14:17]
	v_mfma_f32_16x16x32_bf16 v[10:13], v[156:159], v[228:231], v[10:13]
	s_setprio 0
	s_setprio 1
	v_mfma_f32_16x16x32_bf16 v[54:57], v[166:169], v[182:185], 0
	v_mfma_f32_16x16x32_bf16 v[50:53], v[174:177], v[182:185], 0
	v_mfma_f32_16x16x32_bf16 v[38:41], v[166:169], v[190:193], 0
	v_mfma_f32_16x16x32_bf16 v[34:37], v[174:177], v[190:193], 0
	v_mfma_f32_16x16x32_bf16 v[22:25], v[166:169], v[198:201], 0
	v_mfma_f32_16x16x32_bf16 v[18:21], v[174:177], v[198:201], 0
	v_mfma_f32_16x16x32_bf16 v[6:9], v[166:169], v[224:227], 0
	v_mfma_f32_16x16x32_bf16 v[2:5], v[174:177], v[224:227], 0
	v_mfma_f32_16x16x32_bf16 v[54:57], v[170:173], v[186:189], v[54:57]
	v_mfma_f32_16x16x32_bf16 v[50:53], v[178:181], v[186:189], v[50:53]
	v_mfma_f32_16x16x32_bf16 v[38:41], v[170:173], v[194:197], v[38:41]
	v_mfma_f32_16x16x32_bf16 v[34:37], v[178:181], v[194:197], v[34:37]
	v_mfma_f32_16x16x32_bf16 v[22:25], v[170:173], v[202:205], v[22:25]
	v_mfma_f32_16x16x32_bf16 v[18:21], v[178:181], v[202:205], v[18:21]
	v_mfma_f32_16x16x32_bf16 v[6:9], v[170:173], v[228:231], v[6:9]
	v_mfma_f32_16x16x32_bf16 v[2:5], v[178:181], v[228:231], v[2:5]
	s_setprio 0
	s_barrier
	s_add_i32 s48, 0, 0x18000
	s_add_i32 s49, 0, 0x1c000
	v_add_u32_e32 v156, s48, v161
	v_add_u32_e32 v165, s49, v161
	ds_read_b128 v[144:147], v156
	ds_read_b128 v[148:151], v156 offset:1024
	ds_read_b128 v[152:155], v156 offset:2048
	ds_read_b128 v[156:159], v156 offset:3072
	ds_read_b128 v[166:169], v165
	ds_read_b128 v[170:173], v165 offset:1024
	ds_read_b128 v[174:177], v165 offset:2048
	ds_read_b128 v[178:181], v165 offset:3072
	s_add_u32 s22, s22, 0x40000
	s_addc_u32 s23, s23, 0
	s_mov_b32 m0, s38
	v_lshl_add_u64 v[236:237], s[22:23], 0, v[130:131]
	ds_read_b128 v[182:185], v164 offset:32768
	ds_read_b128 v[186:189], v164 offset:33792
	ds_read_b128 v[190:193], v164 offset:34816
	ds_read_b128 v[194:197], v164 offset:35840
	ds_read_b128 v[198:201], v164 offset:36864
	ds_read_b128 v[202:205], v164 offset:37888
	ds_read_b128 v[224:227], v164 offset:38912
	ds_read_b128 v[228:231], v164 offset:39936
	global_load_lds_dwordx4 v[236:237], off
	v_lshl_add_u64 v[236:237], s[22:23], 0, v[132:133]
	s_mov_b32 m0, s39
	s_nop 0
	global_load_lds_dwordx4 v[236:237], off
	s_waitcnt vmcnt(8)
	s_waitcnt lgkmcnt(0)
	s_barrier
	s_setprio 1
	s_waitcnt lgkmcnt(0)
	v_mfma_f32_16x16x32_bf16 v[126:129], v[144:147], v[182:185], v[126:129]
	v_mfma_f32_16x16x32_bf16 v[122:125], v[152:155], v[182:185], v[122:125]
	v_mfma_f32_16x16x32_bf16 v[110:113], v[144:147], v[190:193], v[110:113]
	v_mfma_f32_16x16x32_bf16 v[106:109], v[152:155], v[190:193], v[106:109]
	v_mfma_f32_16x16x32_bf16 v[94:97], v[144:147], v[198:201], v[94:97]
	v_mfma_f32_16x16x32_bf16 v[90:93], v[152:155], v[198:201], v[90:93]
	v_mfma_f32_16x16x32_bf16 v[78:81], v[144:147], v[224:227], v[78:81]
	v_mfma_f32_16x16x32_bf16 v[74:77], v[152:155], v[224:227], v[74:77]
	v_mfma_f32_16x16x32_bf16 v[126:129], v[148:151], v[186:189], v[126:129]
	v_mfma_f32_16x16x32_bf16 v[122:125], v[156:159], v[186:189], v[122:125]
	v_mfma_f32_16x16x32_bf16 v[110:113], v[148:151], v[194:197], v[110:113]
	v_mfma_f32_16x16x32_bf16 v[106:109], v[156:159], v[194:197], v[106:109]
	v_mfma_f32_16x16x32_bf16 v[94:97], v[148:151], v[202:205], v[94:97]
	v_mfma_f32_16x16x32_bf16 v[90:93], v[156:159], v[202:205], v[90:93]
	v_mfma_f32_16x16x32_bf16 v[78:81], v[148:151], v[228:231], v[78:81]
	v_mfma_f32_16x16x32_bf16 v[74:77], v[156:159], v[228:231], v[74:77]
	s_setprio 0
	s_setprio 1
	v_mfma_f32_16x16x32_bf16 v[118:121], v[166:169], v[182:185], v[118:121]
	v_mfma_f32_16x16x32_bf16 v[114:117], v[174:177], v[182:185], v[114:117]
	v_mfma_f32_16x16x32_bf16 v[102:105], v[166:169], v[190:193], v[102:105]
	v_mfma_f32_16x16x32_bf16 v[98:101], v[174:177], v[190:193], v[98:101]
	v_mfma_f32_16x16x32_bf16 v[86:89], v[166:169], v[198:201], v[86:89]
	v_mfma_f32_16x16x32_bf16 v[82:85], v[174:177], v[198:201], v[82:85]
	v_mfma_f32_16x16x32_bf16 v[70:73], v[166:169], v[224:227], v[70:73]
	v_mfma_f32_16x16x32_bf16 v[66:69], v[174:177], v[224:227], v[66:69]
	v_mfma_f32_16x16x32_bf16 v[118:121], v[170:173], v[186:189], v[118:121]
	v_mfma_f32_16x16x32_bf16 v[114:117], v[178:181], v[186:189], v[114:117]
	v_mfma_f32_16x16x32_bf16 v[102:105], v[170:173], v[194:197], v[102:105]
	v_mfma_f32_16x16x32_bf16 v[98:101], v[178:181], v[194:197], v[98:101]
	v_mfma_f32_16x16x32_bf16 v[86:89], v[170:173], v[202:205], v[86:89]
	v_mfma_f32_16x16x32_bf16 v[82:85], v[178:181], v[202:205], v[82:85]
	v_mfma_f32_16x16x32_bf16 v[70:73], v[170:173], v[228:231], v[70:73]
	v_mfma_f32_16x16x32_bf16 v[66:69], v[178:181], v[228:231], v[66:69]
	s_setprio 0
	s_barrier
; #define PG8_STAGE(bufoff, gbase, voff) do { _Pragma("unroll") for (int _i = 0; _i < 2; ++_i) \
;         __builtin_amdgcn_global_load_lds((const unsigned*)((const char*)(gbase) + (voff)[_i]), (PG8_LAS unsigned*)(lds + (bufoff) + ldsw + _i * 8192), 16, 0, 0); } while (0)
; #define PG8_LDA(dst, b, h) do { _Pragma("unroll") for (int m = 0; m < 4; ++m) _Pragma("unroll") for (int k = 0; k < 2; ++k) dst[m][k] = *(const PG8_LAS bf16x8*)(lds + PG8_SA(b, h) + aoff + m * 2048 + k * 1024); } while (0)
; #define PG8_MMA(ai, bj, At, Bt) do { __builtin_amdgcn_s_setprio(1); _Pragma("unroll") for (int m = 0; m < 4; ++m) _Pragma("unroll") for (int n = 0; n < 2; ++n) _Pragma("unroll") for (int k = 0; k < 2; ++k) \
;         acc[ai][bj][m][n] = __builtin_amdgcn_mfma_f32_16x16x32_bf16(Bt[n][k], At[m][k], acc[ai][bj][m][n], 0, 0, 0); __builtin_amdgcn_s_setprio(0); } while (0)
; #define PG8_WAIT_V(n) asm volatile("s_waitcnt vmcnt(" #n ")" ::: "memory")
; #define PG8_WAIT_L(n) asm volatile("s_waitcnt lgkmcnt(" #n ")" ::: "memory")
; #define PG8_BAR __builtin_amdgcn_s_barrier()
; #define PG8_SCHED __builtin_amdgcn_sched_barrier(0)
; template <class Epi, class Sched, bool ALIGN_EPI = false, bool SP2 = false>
; __device__ __forceinline__ void gemm_phase(PG8_LAS unsigned char* lds, const Gemm g, const Sched& S, const Epi& E) {
;     ...
;         for (int t = 0; t < nt; t += 2) {
;             const bool last = (t == nt - 2);
;             const char* a1 = cA + (size_t)(t + 1) * kstep;
;             const char* a2 = last ? nA : cA + (size_t)(t + 2) * kstep; const char* b2 = last ? nB : cB + (size_t)(t + 2) * kstep;
;             const char* a3 = a2 + kstep; const char* b3 = b2 + kstep;
;     ...
;             PG8_LDA(At, 1, 1); PG8_STAGE(PG8_SB(1, 0), b3, voffB); PG8_STAGE(PG8_SB(1, 1), b3 + hstep, voffB); PG8_STAGE(PG8_SA(1, 0), a3, voffA);
;             PG8_WAIT_V(8); PG8_WAIT_L(0); PG8_BAR; PG8_MMA(1, 0, At, B0); PG8_MMA(1, 1, At, B1); PG8_BAR; PG8_SCHED;
	s_add_i32 s22, s48, s26
	v_lshl_add_u64 v[138:139], v[138:139], 0, s[86:87]
	s_mov_b32 m0, s22
	ds_read_b128 v[182:185], v164 offset:49152
	ds_read_b128 v[186:189], v164 offset:50176
	ds_read_b128 v[190:193], v164 offset:51200
	ds_read_b128 v[194:197], v164 offset:52224
	ds_read_b128 v[198:201], v164 offset:53248
	ds_read_b128 v[202:205], v164 offset:54272
	ds_read_b128 v[224:227], v164 offset:55296
	ds_read_b128 v[228:231], v164 offset:56320
	global_load_lds_dwordx4 v[138:139], off
	s_add_i32 m0, s22, 0x2000
	s_add_u32 s20, s20, 0x40080
	v_lshl_add_u64 v[138:139], v[140:141], 0, s[86:87]
	s_addc_u32 s21, s21, 0
	s_add_i32 s22, s49, s26
	global_load_lds_dwordx4 v[138:139], off
	v_lshl_add_u64 v[138:139], s[20:21], 0, v[0:1]
	s_mov_b32 m0, s22
	s_nop 0
	global_load_lds_dwordx4 v[138:139], off
	v_lshl_add_u64 v[138:139], s[20:21], 0, v[134:135]
	s_add_i32 m0, s22, 0x2000
	s_nop 0
	global_load_lds_dwordx4 v[138:139], off
	v_lshl_add_u64 v[138:139], v[232:233], 0, s[86:87]
	s_mov_b32 m0, s41
	s_nop 0
	global_load_lds_dwordx4 v[138:139], off
	v_lshl_add_u64 v[138:139], v[234:235], 0, s[86:87]
	s_mov_b32 m0, s42
	s_nop 0
	global_load_lds_dwordx4 v[138:139], off
	s_waitcnt vmcnt(8)
	s_waitcnt lgkmcnt(0)
	s_barrier
	s_setprio 1
	s_waitcnt lgkmcnt(0)
	v_mfma_f32_16x16x32_bf16 v[62:65], v[144:147], v[182:185], v[62:65]
	v_mfma_f32_16x16x32_bf16 v[58:61], v[152:155], v[182:185], v[58:61]
	v_mfma_f32_16x16x32_bf16 v[46:49], v[144:147], v[190:193], v[46:49]
	v_mfma_f32_16x16x32_bf16 v[42:45], v[152:155], v[190:193], v[42:45]
	v_mfma_f32_16x16x32_bf16 v[30:33], v[144:147], v[198:201], v[30:33]
	v_mfma_f32_16x16x32_bf16 v[26:29], v[152:155], v[198:201], v[26:29]
	v_mfma_f32_16x16x32_bf16 v[14:17], v[144:147], v[224:227], v[14:17]
	v_mfma_f32_16x16x32_bf16 v[10:13], v[152:155], v[224:227], v[10:13]
	v_mfma_f32_16x16x32_bf16 v[62:65], v[148:151], v[186:189], v[62:65]
	v_mfma_f32_16x16x32_bf16 v[58:61], v[156:159], v[186:189], v[58:61]
	v_mfma_f32_16x16x32_bf16 v[46:49], v[148:151], v[194:197], v[46:49]
	v_mfma_f32_16x16x32_bf16 v[42:45], v[156:159], v[194:197], v[42:45]
	v_mfma_f32_16x16x32_bf16 v[30:33], v[148:151], v[202:205], v[30:33]
	v_mfma_f32_16x16x32_bf16 v[26:29], v[156:159], v[202:205], v[26:29]
	v_mfma_f32_16x16x32_bf16 v[14:17], v[148:151], v[228:231], v[14:17]
	v_mfma_f32_16x16x32_bf16 v[10:13], v[156:159], v[228:231], v[10:13]
	s_setprio 0
	s_setprio 1
	v_mfma_f32_16x16x32_bf16 v[54:57], v[166:169], v[182:185], v[54:57]
	v_mfma_f32_16x16x32_bf16 v[50:53], v[174:177], v[182:185], v[50:53]
	v_mfma_f32_16x16x32_bf16 v[38:41], v[166:169], v[190:193], v[38:41]
	v_mfma_f32_16x16x32_bf16 v[34:37], v[174:177], v[190:193], v[34:37]
	v_mfma_f32_16x16x32_bf16 v[22:25], v[166:169], v[198:201], v[22:25]
	v_mfma_f32_16x16x32_bf16 v[18:21], v[174:177], v[198:201], v[18:21]
	v_mfma_f32_16x16x32_bf16 v[6:9], v[166:169], v[224:227], v[6:9]
	v_mfma_f32_16x16x32_bf16 v[2:5], v[174:177], v[224:227], v[2:5]
	v_mfma_f32_16x16x32_bf16 v[54:57], v[170:173], v[186:189], v[54:57]
	v_mfma_f32_16x16x32_bf16 v[50:53], v[178:181], v[186:189], v[50:53]
	v_mfma_f32_16x16x32_bf16 v[38:41], v[170:173], v[194:197], v[38:41]
	v_mfma_f32_16x16x32_bf16 v[34:37], v[178:181], v[194:197], v[34:37]
	v_mfma_f32_16x16x32_bf16 v[22:25], v[170:173], v[202:205], v[22:25]
	v_mfma_f32_16x16x32_bf16 v[18:21], v[178:181], v[202:205], v[18:21]
	v_mfma_f32_16x16x32_bf16 v[6:9], v[170:173], v[228:231], v[6:9]
	v_mfma_f32_16x16x32_bf16 v[2:5], v[178:181], v[228:231], v[2:5]
	s_setprio 0
	s_barrier
	s_add_i32 s47, s47, 2
	s_add_u32 s8, s8, 0x100
	s_addc_u32 s9, s9, 0
	s_add_u32 s45, s45, 0x100
	s_addc_u32 s46, s46, 0
	s_cmp_gt_u32 s47, 13
	s_cbranch_scc1 .Lpeel_exit_pj

; #define PG8_BAR __builtin_amdgcn_s_barrier()
; template <class Epi, class Sched, bool ALIGN_EPI = false, bool SP2 = false>
; __device__ __forceinline__ void gemm_phase(PG8_LAS unsigned char* lds, const Gemm g, const Sched& S, const Epi& E) {
;     ...
;         if constexpr (ALIGN_EPI) { if (wr == 0) PG8_BAR; }
;         if constexpr (!Epi::AFTER_DRAIN) { E(acc, cur, wr, wc, fr, fq); S.done(cur); }
;     __device__ __forceinline__ void operator()(const f32x4 (&acc)[2][2][4][2], const Unit& u, int wr, int wc, int fr, int fq) const {
;     ...
;             for (int m = 0; m < 4; ++m) {
;                 const int row = row0 + ai * 128 + m * 16; const float rs = (u.pm == pm0) ? RS[row & 255] : row_rstd(ss, row);
.Lpeel_exit_pj:
	ds_read_b32 v224, v162
	ds_read_b32 v225, v162 offset:64
	ds_read_b32 v226, v162 offset:128
	ds_read_b32 v227, v162 offset:192
	ds_read_b32 v228, v162 offset:512
	ds_read_b32 v229, v162 offset:576
	ds_read_b32 v230, v162 offset:640
	ds_read_b32 v231, v162 offset:704
	s_and_b64 vcc, exec, s[10:11]
	s_cbranch_vccz .LBB0_495
	s_barrier
